# A tile loop hot-path layout: bias, masked-tile and rescale blocks moved out of line behind inverted branches; common tile has no taken branch except loop edges
# speedup vs baseline: 1.0003x; 1.0003x over previous
; #define SBAR() __builtin_amdgcn_sched_barrier(0)
; #define PIN(x) asm volatile("" : "+v"(x))
; #define LDV(j_) do { if ((j_) < 4 * NDB) { const lds_cptr a_ = vp + ((j_) % NDB) * 4096 + ((j_) / NDB) * 1024; const s16x4 lo_ = vtr(a_), hi_ = vtr(a_ + 512); \
;             vq[(j_) & 3] = (bf16x8){lo_[0], lo_[1], lo_[2], lo_[3], hi_[0], hi_[1], hi_[2], hi_[3]}; } } while (0)
; #define PVM(j_) o[(j_) % NDB] = MF(vq[(j_) & 3], pw[(j_) / NDB], o[(j_) % NDB])
; #define E4(a_, W_, j_) do { pa1[a_] = EX(pa1[a_]); pa1[a_ + 1] = EX(pa1[a_ + 1]); sacc += pa1[a_]; sacc += pa1[a_ + 1]; W_[j_] = cvtpk(pa1[a_], pa1[a_ + 1]); } while (0)
; template <int KIND> DI void attn_unit(const Params& P, int b, int h, int qb, char* shm, float lam, bool dry = false) {
;     ...
;         if (NDB == 4) {
;             LDV(3); PVM(0); E4(0, w0, 0); PIN(pa1); PIN(sacc); PIN(w0); SBAR();
;             LDV(4); PVM(1); E4(2, w0, 1); PIN(pa1); PIN(sacc); PIN(w0); SBAR();
;             LDV(5); PVM(2); E4(4, w0, 2); PIN(pa1); PIN(sacc); PIN(w0); SBAR();
;             LDV(6); PVM(3); E4(6, w0, 3); PIN(pa1); PIN(sacc); PIN(w0); SBAR();
;             LDV(7); PVM(4); E4(8, w1, 0); PIN(pa1); PIN(sacc); PIN(w1); SBAR();
;             LDV(8); PVM(5); E4(10, w1, 1); PIN(pa1); PIN(sacc); PIN(w1); SBAR();
;             LDV(9); PVM(6); E4(12, w1, 2); PIN(pa1); PIN(sacc); PIN(w1); SBAR();
;             LDV(10); PVM(7); E4(14, w1, 3); PIN(pa1); PIN(sacc); PIN(w1); SBAR();
;         } else {
;             LDV(3); PVM(0); E4(0, w0, 0); E4(2, w0, 1); PIN(pa1); PIN(sacc); PIN(w0); SBAR();
;             LDV(4); PVM(1); E4(4, w0, 2); E4(6, w0, 3); PIN(pa1); PIN(sacc); PIN(w0); SBAR();
;             LDV(5); PVM(2); E4(8, w1, 0); E4(10, w1, 1); PIN(pa1); PIN(sacc); PIN(w1); SBAR();
;             LDV(6); PVM(3); E4(12, w1, 2); E4(14, w1, 3); PIN(pa1); PIN(sacc); PIN(w1); SBAR();
;         }
;     ...
;         pw[2] = __builtin_bit_cast(bf16x8, w0); pw[3] = __builtin_bit_cast(bf16x8, w1);
;         lsum += sacc;
;         ATT_FIX(pb0, pb1, ATT_TILE(i + 1));
.Lat1_nd1:
	v_exp_f32_e32 v86, v86
	ds_read_b64_tr_b16 v[112:113], v190 offset:17408
	ds_read_b64_tr_b16 v[114:115], v190 offset:17920
	v_exp_f32_e32 v87, v87
	v_add_f32_e32 v109, v180, v86
	v_add_f32_e32 v172, v87, v109
	v_cvt_pk_bf16_f32 v109, v86, v87
	s_waitcnt lgkmcnt(4)
	v_mfma_f32_32x32x16_bf16 v[36:51], v[100:103], v[164:167], v[36:51]
	v_exp_f32_e32 v88, v88
	ds_read_b64_tr_b16 v[176:177], v190 offset:21504
	ds_read_b64_tr_b16 v[178:179], v190 offset:22016
	v_exp_f32_e32 v89, v89
	v_add_f32_e32 v100, v172, v88
	v_add_f32_e32 v172, v89, v100
	v_cvt_pk_bf16_f32 v110, v88, v89
	s_waitcnt lgkmcnt(4)
	v_mfma_f32_32x32x16_bf16 v[20:35], v[104:107], v[164:167], v[20:35]
	v_exp_f32_e32 v90, v90
	v_exp_f32_e32 v91, v91
	ds_read_b64_tr_b16 v[100:101], v190 offset:25600
	ds_read_b64_tr_b16 v[102:103], v190 offset:26112
	v_add_f32_e32 v104, v172, v90
	v_cvt_pk_bf16_f32 v111, v90, v91
	v_add_f32_e32 v172, v91, v104
	s_waitcnt lgkmcnt(4)
	v_mfma_f32_32x32x16_bf16 v[68:83], v[112:115], v[168:171], v[68:83]
	v_exp_f32_e32 v92, v92
	v_exp_f32_e32 v93, v93
	ds_read_b64_tr_b16 v[104:105], v190 offset:29696
	ds_read_b64_tr_b16 v[106:107], v190 offset:30208
	v_add_f32_e32 v164, v172, v92
	v_add_f32_e32 v180, v93, v164
	v_cvt_pk_bf16_f32 v112, v92, v93
	s_waitcnt lgkmcnt(4)
	v_mfma_f32_32x32x16_bf16 v[52:67], v[176:179], v[168:171], v[52:67]
	v_exp_f32_e32 v94, v94
	ds_read_b64_tr_b16 v[172:173], v190 offset:18432
	ds_read_b64_tr_b16 v[174:175], v190 offset:18944
	v_exp_f32_e32 v95, v95
	v_add_f32_e32 v165, v180, v94
	v_add_f32_e32 v166, v95, v165
	v_cvt_pk_bf16_f32 v113, v94, v95
	s_waitcnt lgkmcnt(4)
	v_mfma_f32_32x32x16_bf16 v[36:51], v[100:103], v[168:171], v[36:51]
	v_exp_f32_e32 v96, v96
	ds_read_b64_tr_b16 v[176:177], v190 offset:22528
	ds_read_b64_tr_b16 v[178:179], v190 offset:23040
	v_exp_f32_e32 v97, v97
	v_add_f32_e32 v100, v166, v96
	v_add_f32_e32 v100, v97, v100
	v_cvt_pk_bf16_f32 v114, v96, v97
	s_waitcnt lgkmcnt(4)
	v_mfma_f32_32x32x16_bf16 v[20:35], v[104:107], v[168:171], v[20:35]
	v_exp_f32_e32 v98, v98
	v_exp_f32_e32 v99, v99
	ds_read_b64_tr_b16 v[180:181], v190 offset:26624
	ds_read_b64_tr_b16 v[182:183], v190 offset:27136
	v_add_f32_e32 v100, v100, v98
	v_cvt_pk_bf16_f32 v115, v98, v99
	v_add_f32_e32 v100, v99, v100
	s_cmp_le_i32 s4, s13
	s_cbranch_scc0 .Lhot1_bias

.Lat1_nd2:
	s_cmp_lt_u32 s3, s7
	s_cbranch_scc0 .Lhot1_mask

; DI float max3f(float a, float b, float c) { float r; asm("v_max3_f32 %0, %1, %2, %3" : "=v"(r) : "v"(a), "v"(b), "v"(c)); return r; }
; DI float swapmax(float m) { auto rr = __builtin_amdgcn_permlane32_swap(__float_as_uint(m), __float_as_uint(m), false, false); return fmaxf(__uint_as_float(rr[0]), __uint_as_float(rr[1])); }
; #define SBAR() __builtin_amdgcn_sched_barrier(0)
; #define PIN(x) asm volatile("" : "+v"(x))
; #define PVM(j_) o[(j_) % NDB] = MF(vq[(j_) & 3], pw[(j_) / NDB], o[(j_) % NDB])
; template <int KIND> DI void attn_unit(const Params& P, int b, int h, int qb, char* shm, float lam, bool dry = false) {
;     ...
;             LDV(11); PVM(8); rm = max3f(pb0[0], pb0[1], pb1[0]); rm2 = max3f(pb0[2], pb0[3], pb1[1]); PIN(rm); PIN(rm2); SBAR();
;             LDV(12); PVM(9); rm = max3f(rm, pb1[2], pb1[3]); rm2 = max3f(rm2, pb0[4], pb0[5]); PIN(rm); PIN(rm2); SBAR();
;             LDV(13); PVM(10); rm = max3f(rm, pb0[6], pb0[7]); rm2 = max3f(rm2, pb1[4], pb1[5]); PIN(rm); PIN(rm2); SBAR();
;             LDV(14); PVM(11); rm = max3f(rm, pb1[6], pb1[7]); rm2 = max3f(rm2, pb0[8], pb0[9]); PIN(rm); PIN(rm2); SBAR();
;             LDV(15); PVM(12); rm = max3f(rm, pb0[10], pb0[11]); rm2 = max3f(rm2, pb1[8], pb1[9]); PIN(rm); PIN(rm2); SBAR();
;             PVM(13); rm = max3f(rm, pb1[10], pb1[11]); rm2 = max3f(rm2, pb0[12], pb0[13]); PIN(rm); PIN(rm2); SBAR();
;             PVM(14); rm = max3f(rm, pb0[14], pb0[15]); rm2 = max3f(rm2, pb1[12], pb1[13]); PIN(rm); PIN(rm2); SBAR();
;             PVM(15); rm = max3f(rm, pb1[14], pb1[15]); PIN(rm); SBAR();
;         } else {
;             LDV(7); PVM(4); rm = max3f(pb0[0], pb0[1], pb1[0]); rm2 = max3f(pb0[2], pb0[3], pb1[1]); rm = max3f(rm, pb1[2], pb1[3]); rm2 = max3f(rm2, pb0[4], pb0[5]); PIN(rm); PIN(rm2); SBAR();
;             PVM(5); rm = max3f(rm, pb0[6], pb0[7]); rm2 = max3f(rm2, pb1[4], pb1[5]); rm = max3f(rm, pb1[6], pb1[7]); rm2 = max3f(rm2, pb0[8], pb0[9]); PIN(rm); PIN(rm2); SBAR();
;             PVM(6); rm = max3f(rm, pb0[10], pb0[11]); rm2 = max3f(rm2, pb1[8], pb1[9]); rm = max3f(rm, pb1[10], pb1[11]); rm2 = max3f(rm2, pb0[12], pb0[13]); PIN(rm); PIN(rm2); SBAR();
;             PVM(7); rm = max3f(rm, pb0[14], pb0[15]); rm2 = max3f(rm2, pb1[12], pb1[13]); rm = max3f(rm, pb1[14], pb1[15]); PIN(rm); PIN(rm2); SBAR();
;         }
;     ...
;         rm = swapmax(max3f(rm, rm2, rm2));
.Lat1_nd3:
	ds_read_b64_tr_b16 v[84:85], v190 offset:31744
	ds_read_b64_tr_b16 v[86:87], v190 offset:32256
	v_max3_f32 v100, v100, v126, v127
	v_max3_f32 v101, v101, v140, v141
	s_waitcnt lgkmcnt(4)
	v_mfma_f32_32x32x16_bf16 v[52:67], v[92:95], v[112:115], v[52:67]
	v_max3_f32 v100, v100, v142, v143
	v_max3_f32 v101, v101, v128, v129
	s_waitcnt lgkmcnt(2)
	v_mfma_f32_32x32x16_bf16 v[36:51], v[96:99], v[112:115], v[36:51]
	v_max3_f32 v100, v100, v130, v131
	v_max3_f32 v101, v101, v144, v145
	v_max3_f32 v100, v100, v146, v147
	v_max3_f32 v100, v100, v101, v101
	v_mov_b32_e32 v101, v100
	s_waitcnt lgkmcnt(0)
	v_mfma_f32_32x32x16_bf16 v[20:35], v[84:87], v[112:115], v[20:35]
	s_add_i32 s3, s3, 1
	s_cmp_ge_u32 s3, s18
	v_permlane32_swap_b32_e32 v100, v101
	s_cbranch_scc1 .LBB0_408


; #define LAS __attribute__((address_space(3)))
; #define SBAR() __builtin_amdgcn_sched_barrier(0)
; template <int KIND> DI void attn_unit(const Params& P, int b, int h, int qb, char* shm, float lam, bool dry = false) {
;     ...
;     f32x16 pa0, pa1, pb0, pb1;
;     bf16x8 kf[4], x0, x1;
;     ATT_KLD(0, 0); ATT_XLD(0);
;     pa0 = MF(kf[0], qr[0], negm); pa1 = MF(kf[1], qr[0], negm); pa0 = MF(kf[2], qr[1], pa0); pa1 = MF(kf[3], qr[1], pa1);
;     SBAR(); ATT_KLD(0, 1); SBAR();
;     pa0 = MF(kf[0], qr[2], pa0); pa1 = MF(kf[1], qr[2], pa1); pa0 = MF(kf[2], qr[3], pa0); pa1 = MF(kf[3], qr[3], pa1);
;     if (KIND == 2) { pa0 = MF(x0, ones, pa0); pa1 = MF(x1, ones, pa1); }
;     ATT_FIX(pa0, pa1, ATT_TILE(0));
;     { float rm = max3f(pa0[0], pa0[1], pa1[0]), rm2 = max3f(pa0[2], pa0[3], pa1[1]); rm = max3f(rm, pa1[2], pa1[3]);
; #pragma unroll
;       for (int r = 4; r < 16; r += 4) { rm = max3f(rm, pa0[r], pa0[r + 1]); rm2 = max3f(rm2, pa0[r + 2], pa0[r + 3]); rm = max3f(rm, pa1[r], pa1[r + 1]); rm2 = max3f(rm2, pa1[r + 2], pa1[r + 3]); }
;       rm = swapmax(max3f(rm, rm2, rm2)); ATT_DECIDE(pa0, pa1, rm); }
;     for (int i = 0; i < nt_eff; ++i) {
;         ATT_STEP_BAR(i);
;         const int sn = (sc == 3 * SLOT) ? 0 : sc + SLOT;
;         const lds_cptr vp = shm3 + sc + 16384 + vlane;
;         bf16x8 vq[4]; bf16x8 pw[4]; u32x4 w0, w1; float sacc = 0.f;
;     ...
;         ATT_KLD(sn, 0); ATT_XLD(sn);
;         SBAR();
;     ...
;         G1(pb0 = MF(kf[0], qr[0], negm), 0, w0, 0);  G1(pb1 = MF(kf[1], qr[0], negm), 2, w0, 1);
;         G1(pb0 = MF(kf[2], qr[1], pb0), 4, w0, 2);   G1(pb1 = MF(kf[3], qr[1], pb1), 6, w0, 3);
;     ...
;         rm = swapmax(max3f(rm, rm2, rm2));
;         if (KIND == 2) {
;             const u32x2 kx = *(const LAS u32x2*)(shm3 + sc + 32768);
;             const float xk0 = __uint_as_float(kx.x << 16) + __uint_as_float(kx.x & 0xffff0000u) + __uint_as_float(kx.y << 16);
;             const float ltot = swapsum(lsum);
;             const bool ok = (qkmax + cb + xk0) < (mhat + __builtin_amdgcn_logf(ltot) - 54.0f);
;             const bool allok = __all(ok) && !(ATT_TILE(i) > wt_hi);
;             if (lane == 0) vote[8 * (i & 3) + wid] = allok ? 1u : 0u;
;         }
;         if (i + 1 < nt_eff) ATT_DECIDE(pb0, pb1, rm);
;         pa0 = pb0; pa1 = pb1;
;         sc = sn; sd = (sd == 3 * SLOT) ? 0 : sd + SLOT;
	v_max_f32_e32 v100, v100, v101
	v_cmp_lt_f32_e32 vcc, s88, v100
	s_cbranch_vccnz .Lhot1_resc
.LBB0_408:
	s_add_i32 s1, s14, 0x8400
	s_cmp_lg_u32 s14, 0x18c00
	s_cselect_b32 s14, s1, 0
	s_add_i32 s4, s4, 64
	v_add_u32_e32 v192, 0x100, v192
	v_lshl_add_u64 v[184:185], v[184:185], 0, s[62:63]
	s_cmp_eq_u32 s3, s18
	v_lshl_add_u64 v[186:187], v[186:187], 0, s[92:93]
	s_cbranch_scc1 .LBB0_412
	s_mov_b32 s5, s0
	s_add_i32 s1, s3, 3
	s_cmp_lt_u32 s1, s18
	s_cselect_b32 s1, 1, 0
	s_add_i32 s0, s5, 0x8400
	s_cmp_lg_u32 s5, 0x18c00
	s_cselect_b32 s0, s0, 0
	v_add_u32_e32 v168, s0, v193
	v_add_u32_e32 v190, s5, v196
	s_cmp_ge_u32 s3, s6
	s_cbranch_scc1 .Lrot2_w0
	s_waitcnt vmcnt(4) lgkmcnt(0)
.Lrot2_bar:
	s_barrier
	ds_read_b128 v[84:87], v168
	ds_read_b128 v[172:175], v168 offset:512
	ds_read_b128 v[176:179], v168 offset:2048
	ds_read_b128 v[180:183], v168 offset:2560
	s_waitcnt lgkmcnt(3)
	v_mfma_f32_32x32x16_bf16 v[100:115], v[84:87], v[160:163], v[4:19]
	v_exp_f32_e32 v116, v116
	v_exp_f32_e32 v117, v117
	v_add_f32_e32 v84, 0, v116
	v_add_f32_e32 v191, v117, v84
	v_cvt_pk_bf16_f32 v164, v116, v117
	s_waitcnt lgkmcnt(2)
	v_mfma_f32_32x32x16_bf16 v[84:99], v[172:175], v[160:163], v[4:19]
	s_cmp_eq_u32 s1, 0
	s_cbranch_scc1 .Lat2_nd0
	s_add_i32 m0, s11, s14
	s_nop 0
	global_load_lds_dwordx4 v[184:185], off

; #define SBAR() __builtin_amdgcn_sched_barrier(0)
; #define PIN(x) asm volatile("" : "+v"(x))
; #define LDV(j_) do { if ((j_) < 4 * NDB) { const lds_cptr a_ = vp + ((j_) % NDB) * 4096 + ((j_) / NDB) * 1024; const s16x4 lo_ = vtr(a_), hi_ = vtr(a_ + 512); \
;             vq[(j_) & 3] = (bf16x8){lo_[0], lo_[1], lo_[2], lo_[3], hi_[0], hi_[1], hi_[2], hi_[3]}; } } while (0)
; #define PVM(j_) o[(j_) % NDB] = MF(vq[(j_) & 3], pw[(j_) / NDB], o[(j_) % NDB])
; #define E4(a_, W_, j_) do { pa1[a_] = EX(pa1[a_]); pa1[a_ + 1] = EX(pa1[a_ + 1]); sacc += pa1[a_]; sacc += pa1[a_ + 1]; W_[j_] = cvtpk(pa1[a_], pa1[a_ + 1]); } while (0)
; template <int KIND> DI void attn_unit(const Params& P, int b, int h, int qb, char* shm, float lam, bool dry = false) {
;     ...
;         if (NDB == 4) {
;             LDV(3); PVM(0); E4(0, w0, 0); PIN(pa1); PIN(sacc); PIN(w0); SBAR();
;             LDV(4); PVM(1); E4(2, w0, 1); PIN(pa1); PIN(sacc); PIN(w0); SBAR();
;             LDV(5); PVM(2); E4(4, w0, 2); PIN(pa1); PIN(sacc); PIN(w0); SBAR();
;             LDV(6); PVM(3); E4(6, w0, 3); PIN(pa1); PIN(sacc); PIN(w0); SBAR();
;             LDV(7); PVM(4); E4(8, w1, 0); PIN(pa1); PIN(sacc); PIN(w1); SBAR();
;             LDV(8); PVM(5); E4(10, w1, 1); PIN(pa1); PIN(sacc); PIN(w1); SBAR();
;             LDV(9); PVM(6); E4(12, w1, 2); PIN(pa1); PIN(sacc); PIN(w1); SBAR();
;             LDV(10); PVM(7); E4(14, w1, 3); PIN(pa1); PIN(sacc); PIN(w1); SBAR();
;         } else {
;             LDV(3); PVM(0); E4(0, w0, 0); E4(2, w0, 1); PIN(pa1); PIN(sacc); PIN(w0); SBAR();
;             LDV(4); PVM(1); E4(4, w0, 2); E4(6, w0, 3); PIN(pa1); PIN(sacc); PIN(w0); SBAR();
;             LDV(5); PVM(2); E4(8, w1, 0); E4(10, w1, 1); PIN(pa1); PIN(sacc); PIN(w1); SBAR();
;             LDV(6); PVM(3); E4(12, w1, 2); E4(14, w1, 3); PIN(pa1); PIN(sacc); PIN(w1); SBAR();
;         }
;     ...
;         pw[2] = __builtin_bit_cast(bf16x8, w0); pw[3] = __builtin_bit_cast(bf16x8, w1);
;         lsum += sacc;
;         ATT_FIX(pb0, pb1, ATT_TILE(i + 1));
.Lat2_nd1:
	v_exp_f32_e32 v134, v134
	ds_read_b64_tr_b16 v[128:129], v190 offset:17408
	ds_read_b64_tr_b16 v[130:131], v190 offset:17920
	v_exp_f32_e32 v135, v135
	v_add_f32_e32 v125, v180, v134
	v_add_f32_e32 v172, v135, v125
	v_cvt_pk_bf16_f32 v125, v134, v135
	s_waitcnt lgkmcnt(4)
	v_mfma_f32_32x32x16_bf16 v[36:51], v[116:119], v[164:167], v[36:51]
	v_exp_f32_e32 v136, v136
	ds_read_b64_tr_b16 v[176:177], v190 offset:21504
	ds_read_b64_tr_b16 v[178:179], v190 offset:22016
	v_exp_f32_e32 v137, v137
	v_add_f32_e32 v116, v172, v136
	v_add_f32_e32 v172, v137, v116
	v_cvt_pk_bf16_f32 v126, v136, v137
	s_waitcnt lgkmcnt(4)
	v_mfma_f32_32x32x16_bf16 v[20:35], v[120:123], v[164:167], v[20:35]
	v_exp_f32_e32 v138, v138
	v_exp_f32_e32 v139, v139
	ds_read_b64_tr_b16 v[116:117], v190 offset:25600
	ds_read_b64_tr_b16 v[118:119], v190 offset:26112
	v_add_f32_e32 v120, v172, v138
	v_cvt_pk_bf16_f32 v127, v138, v139
	v_add_f32_e32 v172, v139, v120
	s_waitcnt lgkmcnt(4)
	v_mfma_f32_32x32x16_bf16 v[68:83], v[128:131], v[168:171], v[68:83]
	v_exp_f32_e32 v140, v140
	v_exp_f32_e32 v141, v141
	ds_read_b64_tr_b16 v[120:121], v190 offset:29696
	ds_read_b64_tr_b16 v[122:123], v190 offset:30208
	v_add_f32_e32 v164, v172, v140
	v_add_f32_e32 v180, v141, v164
	v_cvt_pk_bf16_f32 v128, v140, v141
	s_waitcnt lgkmcnt(4)
	v_mfma_f32_32x32x16_bf16 v[52:67], v[176:179], v[168:171], v[52:67]
	v_exp_f32_e32 v142, v142
	ds_read_b64_tr_b16 v[172:173], v190 offset:18432
	ds_read_b64_tr_b16 v[174:175], v190 offset:18944
	v_exp_f32_e32 v143, v143
	v_add_f32_e32 v165, v180, v142
	v_add_f32_e32 v166, v143, v165
	v_cvt_pk_bf16_f32 v129, v142, v143
	s_waitcnt lgkmcnt(4)
	v_mfma_f32_32x32x16_bf16 v[36:51], v[116:119], v[168:171], v[36:51]
	v_exp_f32_e32 v144, v144
	ds_read_b64_tr_b16 v[176:177], v190 offset:22528
	ds_read_b64_tr_b16 v[178:179], v190 offset:23040
	v_exp_f32_e32 v145, v145
	v_add_f32_e32 v116, v166, v144
	v_add_f32_e32 v116, v145, v116
	v_cvt_pk_bf16_f32 v130, v144, v145
	s_waitcnt lgkmcnt(4)
	v_mfma_f32_32x32x16_bf16 v[20:35], v[120:123], v[168:171], v[20:35]
	v_exp_f32_e32 v146, v146
	v_exp_f32_e32 v147, v147
	ds_read_b64_tr_b16 v[180:181], v190 offset:26624
	ds_read_b64_tr_b16 v[182:183], v190 offset:27136
	v_add_f32_e32 v116, v116, v146
	v_cvt_pk_bf16_f32 v131, v146, v147
	v_add_f32_e32 v116, v147, v116
	s_cmp_le_i32 s4, s13
	s_cbranch_scc0 .Lhot2_bias

; DI float max3f(float a, float b, float c) { float r; asm("v_max3_f32 %0, %1, %2, %3" : "=v"(r) : "v"(a), "v"(b), "v"(c)); return r; }
; DI float swapmax(float m) { auto rr = __builtin_amdgcn_permlane32_swap(__float_as_uint(m), __float_as_uint(m), false, false); return fmaxf(__uint_as_float(rr[0]), __uint_as_float(rr[1])); }
; #define SBAR() __builtin_amdgcn_sched_barrier(0)
; #define PIN(x) asm volatile("" : "+v"(x))
; #define PVM(j_) o[(j_) % NDB] = MF(vq[(j_) & 3], pw[(j_) / NDB], o[(j_) % NDB])
; template <int KIND> DI void attn_unit(const Params& P, int b, int h, int qb, char* shm, float lam, bool dry = false) {
;     ...
;             LDV(11); PVM(8); rm = max3f(pb0[0], pb0[1], pb1[0]); rm2 = max3f(pb0[2], pb0[3], pb1[1]); PIN(rm); PIN(rm2); SBAR();
;             LDV(12); PVM(9); rm = max3f(rm, pb1[2], pb1[3]); rm2 = max3f(rm2, pb0[4], pb0[5]); PIN(rm); PIN(rm2); SBAR();
;             LDV(13); PVM(10); rm = max3f(rm, pb0[6], pb0[7]); rm2 = max3f(rm2, pb1[4], pb1[5]); PIN(rm); PIN(rm2); SBAR();
;             LDV(14); PVM(11); rm = max3f(rm, pb1[6], pb1[7]); rm2 = max3f(rm2, pb0[8], pb0[9]); PIN(rm); PIN(rm2); SBAR();
;             LDV(15); PVM(12); rm = max3f(rm, pb0[10], pb0[11]); rm2 = max3f(rm2, pb1[8], pb1[9]); PIN(rm); PIN(rm2); SBAR();
;             PVM(13); rm = max3f(rm, pb1[10], pb1[11]); rm2 = max3f(rm2, pb0[12], pb0[13]); PIN(rm); PIN(rm2); SBAR();
;             PVM(14); rm = max3f(rm, pb0[14], pb0[15]); rm2 = max3f(rm2, pb1[12], pb1[13]); PIN(rm); PIN(rm2); SBAR();
;             PVM(15); rm = max3f(rm, pb1[14], pb1[15]); PIN(rm); SBAR();
;         } else {
;             LDV(7); PVM(4); rm = max3f(pb0[0], pb0[1], pb1[0]); rm2 = max3f(pb0[2], pb0[3], pb1[1]); rm = max3f(rm, pb1[2], pb1[3]); rm2 = max3f(rm2, pb0[4], pb0[5]); PIN(rm); PIN(rm2); SBAR();
;             PVM(5); rm = max3f(rm, pb0[6], pb0[7]); rm2 = max3f(rm2, pb1[4], pb1[5]); rm = max3f(rm, pb1[6], pb1[7]); rm2 = max3f(rm2, pb0[8], pb0[9]); PIN(rm); PIN(rm2); SBAR();
;             PVM(6); rm = max3f(rm, pb0[10], pb0[11]); rm2 = max3f(rm2, pb1[8], pb1[9]); rm = max3f(rm, pb1[10], pb1[11]); rm2 = max3f(rm2, pb0[12], pb0[13]); PIN(rm); PIN(rm2); SBAR();
;             PVM(7); rm = max3f(rm, pb0[14], pb0[15]); rm2 = max3f(rm2, pb1[12], pb1[13]); rm = max3f(rm, pb1[14], pb1[15]); PIN(rm); PIN(rm2); SBAR();
;         }
;     ...
;         rm = swapmax(max3f(rm, rm2, rm2));
.Lat2_nd3:
	ds_read_b64_tr_b16 v[132:133], v190 offset:31744
	ds_read_b64_tr_b16 v[134:135], v190 offset:32256
	v_max3_f32 v116, v116, v110, v111
	v_max3_f32 v117, v117, v92, v93
	s_waitcnt lgkmcnt(4)
	v_mfma_f32_32x32x16_bf16 v[52:67], v[140:143], v[128:131], v[52:67]
	v_max3_f32 v116, v116, v94, v95
	v_max3_f32 v117, v117, v112, v113
	s_waitcnt lgkmcnt(2)
	v_mfma_f32_32x32x16_bf16 v[36:51], v[144:147], v[128:131], v[36:51]
	v_max3_f32 v116, v116, v114, v115
	v_max3_f32 v117, v117, v96, v97
	v_max3_f32 v116, v116, v98, v99
	v_max3_f32 v116, v116, v117, v117
	v_mov_b32_e32 v117, v116
	s_waitcnt lgkmcnt(0)
	v_mfma_f32_32x32x16_bf16 v[20:35], v[132:135], v[128:131], v[20:35]
	s_add_i32 s3, s3, 1
	s_cmp_ge_u32 s3, s18
	v_permlane32_swap_b32_e32 v116, v117
	s_cbranch_scc1 .Lat2_408


; #define LAS __attribute__((address_space(3)))
; DI float max3f(float a, float b, float c) { float r; asm("v_max3_f32 %0, %1, %2, %3" : "=v"(r) : "v"(a), "v"(b), "v"(c)); return r; }
; DI float swapmax(float m) { auto rr = __builtin_amdgcn_permlane32_swap(__float_as_uint(m), __float_as_uint(m), false, false); return fmaxf(__uint_as_float(rr[0]), __uint_as_float(rr[1])); }
; DI float swapsum(float m) { auto rr = __builtin_amdgcn_permlane32_swap(__float_as_uint(m), __float_as_uint(m), false, false); return __uint_as_float(rr[0]) + __uint_as_float(rr[1]); }
; #define ATT_DECIDE(P0, P1, rm_) do { if (__any((rm_) > 6.0f)) { const float dl = fmaxf((rm_), 0.f); mhat += dl; const float f = EX(-dl); lsum *= f; \
;             _Pragma("unroll") for (int r = 0; r < 16; ++r) { P0[r] -= dl; P1[r] -= dl; negm[r] -= dl; } \
;             _Pragma("unroll") for (int i2 = 0; i2 < NDB; ++i2) _Pragma("unroll") for (int r = 0; r < 16; ++r) o[i2][r] *= f; } } while (0)
; template <int KIND> DI void attn_unit(const Params& P, int b, int h, int qb, char* shm, float lam, bool dry = false) {
;     ...
;         rm = swapmax(max3f(rm, rm2, rm2));
;         if (KIND == 2) {
;             const u32x2 kx = *(const LAS u32x2*)(shm3 + sc + 32768);
;             const float xk0 = __uint_as_float(kx.x << 16) + __uint_as_float(kx.x & 0xffff0000u) + __uint_as_float(kx.y << 16);
;             const float ltot = swapsum(lsum);
;             const bool ok = (qkmax + cb + xk0) < (mhat + __builtin_amdgcn_logf(ltot) - 54.0f);
;             const bool allok = __all(ok) && !(ATT_TILE(i) > wt_hi);
;             if (lane == 0) vote[8 * (i & 3) + wid] = allok ? 1u : 0u;
;         }
;         if (i + 1 < nt_eff) ATT_DECIDE(pb0, pb1, rm);
	v_max_f32_e32 v116, v116, v117
	v_cmp_lt_f32_e32 vcc, s88, v116
	s_cbranch_vccnz .Lhot2_resc

.Lhot1_bias:
	ds_read2_b32 v[84:85], v192 offset1:1
	ds_read2_b32 v[86:87], v192 offset0:2 offset1:3
	ds_read2_b32 v[88:89], v192 offset0:8 offset1:9
	ds_read2_b32 v[90:91], v192 offset0:10 offset1:11
	ds_read2_b32 v[92:93], v192 offset0:16 offset1:17
	ds_read2_b32 v[94:95], v192 offset0:18 offset1:19
	ds_read2_b32 v[96:97], v192 offset0:24 offset1:25
	ds_read2_b32 v[98:99], v192 offset0:26 offset1:27
	ds_read2_b32 v[102:103], v192 offset0:32 offset1:33
	ds_read2_b32 v[104:105], v192 offset0:34 offset1:35
	ds_read2_b32 v[106:107], v192 offset0:40 offset1:41
	ds_read2_b32 v[164:165], v192 offset0:42 offset1:43
	s_waitcnt lgkmcnt(11)
	v_pk_add_f32 v[116:117], v[116:117], v[84:85]
	s_waitcnt lgkmcnt(5)
	v_pk_add_f32 v[128:129], v[128:129], v[96:97]
	v_pk_add_f32 v[126:127], v[126:127], v[94:95]
	v_pk_add_f32 v[124:125], v[124:125], v[92:93]
	ds_read2_b32 v[84:85], v192 offset0:48 offset1:49
	ds_read2_b32 v[92:93], v192 offset0:50 offset1:51
	ds_read2_b32 v[94:95], v192 offset0:56 offset1:57
	ds_read2_b32 v[96:97], v192 offset0:58 offset1:59
	s_waitcnt lgkmcnt(8)
	v_pk_add_f32 v[130:131], v[130:131], v[98:99]
	v_pk_add_f32 v[122:123], v[122:123], v[90:91]
	v_pk_add_f32 v[120:121], v[120:121], v[88:89]
	v_pk_add_f32 v[118:119], v[118:119], v[86:87]
	s_waitcnt lgkmcnt(7)
	v_pk_add_f32 v[132:133], v[132:133], v[102:103]
	s_waitcnt lgkmcnt(0)
	v_pk_add_f32 v[146:147], v[146:147], v[96:97]
	v_pk_add_f32 v[144:145], v[144:145], v[94:95]
	v_pk_add_f32 v[142:143], v[142:143], v[92:93]
	v_pk_add_f32 v[140:141], v[140:141], v[84:85]
	v_pk_add_f32 v[138:139], v[138:139], v[164:165]
	v_pk_add_f32 v[136:137], v[136:137], v[106:107]
	v_pk_add_f32 v[134:135], v[134:135], v[104:105]
	s_branch .LBB0_405
.Lhot1_mask:
	v_mov_b32_e32 v116, v245
	v_mov_b32_e32 v117, v245
	v_mov_b32_e32 v118, v245
	v_mov_b32_e32 v119, v245
	v_mov_b32_e32 v120, v245
	v_mov_b32_e32 v121, v245
	v_mov_b32_e32 v122, v245
	v_mov_b32_e32 v123, v245
	v_mov_b32_e32 v124, v245
	v_mov_b32_e32 v125, v245
	v_mov_b32_e32 v126, v245
	v_mov_b32_e32 v127, v245
	v_mov_b32_e32 v128, v245
	v_mov_b32_e32 v129, v245
	v_mov_b32_e32 v130, v245
	v_mov_b32_e32 v131, v245
	v_mov_b32_e32 v132, v245
	v_mov_b32_e32 v133, v245
	v_mov_b32_e32 v134, v245
	v_mov_b32_e32 v135, v245
	v_mov_b32_e32 v136, v245
	v_mov_b32_e32 v137, v245
	v_mov_b32_e32 v138, v245
	v_mov_b32_e32 v139, v245
	v_mov_b32_e32 v140, v245
	v_mov_b32_e32 v141, v245
	v_mov_b32_e32 v142, v245
	v_mov_b32_e32 v143, v245
	v_mov_b32_e32 v144, v245
	v_mov_b32_e32 v145, v245
	v_mov_b32_e32 v146, v245
	v_mov_b32_e32 v147, v245
	s_branch .Lat1_nomask
.Lhot1_resc:
	v_max_f32_e32 v100, v100, v100
	v_max_f32_e32 v101, 0, v100
	v_exp_f32_e64 v100, -v101
	v_sub_f32_e32 v131, v131, v101
	v_sub_f32_e32 v130, v130, v101
	v_sub_f32_e32 v129, v129, v101
	v_pk_mul_f32 v[82:83], v[82:83], v[100:101] op_sel_hi:[1,0]
	v_pk_mul_f32 v[80:81], v[80:81], v[100:101] op_sel_hi:[1,0]
	v_pk_mul_f32 v[78:79], v[78:79], v[100:101] op_sel_hi:[1,0]
	v_pk_mul_f32 v[76:77], v[76:77], v[100:101] op_sel_hi:[1,0]
	v_pk_mul_f32 v[74:75], v[74:75], v[100:101] op_sel_hi:[1,0]
	v_pk_mul_f32 v[72:73], v[72:73], v[100:101] op_sel_hi:[1,0]
	v_pk_mul_f32 v[70:71], v[70:71], v[100:101] op_sel_hi:[1,0]
	v_pk_mul_f32 v[68:69], v[68:69], v[100:101] op_sel_hi:[1,0]
	v_pk_mul_f32 v[66:67], v[66:67], v[100:101] op_sel_hi:[1,0]
	v_pk_mul_f32 v[64:65], v[64:65], v[100:101] op_sel_hi:[1,0]
	v_pk_mul_f32 v[62:63], v[62:63], v[100:101] op_sel_hi:[1,0]
	v_pk_mul_f32 v[60:61], v[60:61], v[100:101] op_sel_hi:[1,0]
	v_pk_mul_f32 v[58:59], v[58:59], v[100:101] op_sel_hi:[1,0]
	v_pk_mul_f32 v[56:57], v[56:57], v[100:101] op_sel_hi:[1,0]
	v_pk_mul_f32 v[54:55], v[54:55], v[100:101] op_sel_hi:[1,0]
	v_pk_mul_f32 v[52:53], v[52:53], v[100:101] op_sel_hi:[1,0]
	v_pk_mul_f32 v[50:51], v[50:51], v[100:101] op_sel_hi:[1,0]
	v_pk_mul_f32 v[48:49], v[48:49], v[100:101] op_sel_hi:[1,0]
	v_pk_mul_f32 v[46:47], v[46:47], v[100:101] op_sel_hi:[1,0]
	v_pk_mul_f32 v[44:45], v[44:45], v[100:101] op_sel_hi:[1,0]
	v_pk_mul_f32 v[42:43], v[42:43], v[100:101] op_sel_hi:[1,0]
	v_pk_mul_f32 v[40:41], v[40:41], v[100:101] op_sel_hi:[1,0]
	v_pk_mul_f32 v[38:39], v[38:39], v[100:101] op_sel_hi:[1,0]
	v_pk_mul_f32 v[36:37], v[36:37], v[100:101] op_sel_hi:[1,0]
	v_pk_mul_f32 v[34:35], v[34:35], v[100:101] op_sel_hi:[1,0]
	v_pk_mul_f32 v[32:33], v[32:33], v[100:101] op_sel_hi:[1,0]
	v_pk_mul_f32 v[30:31], v[30:31], v[100:101] op_sel_hi:[1,0]
	v_pk_mul_f32 v[28:29], v[28:29], v[100:101] op_sel_hi:[1,0]
	v_pk_mul_f32 v[26:27], v[26:27], v[100:101] op_sel_hi:[1,0]
	v_pk_mul_f32 v[24:25], v[24:25], v[100:101] op_sel_hi:[1,0]
	v_pk_mul_f32 v[22:23], v[22:23], v[100:101] op_sel_hi:[1,0]
	v_pk_mul_f32 v[20:21], v[20:21], v[100:101] op_sel_hi:[1,0]
	v_sub_f32_e32 v128, v128, v101
	v_sub_f32_e32 v127, v127, v101
	v_sub_f32_e32 v126, v126, v101
	v_sub_f32_e32 v125, v125, v101
	v_sub_f32_e32 v124, v124, v101
	v_sub_f32_e32 v123, v123, v101
	v_sub_f32_e32 v122, v122, v101
	v_sub_f32_e32 v121, v121, v101
	v_sub_f32_e32 v120, v120, v101
	v_sub_f32_e32 v119, v119, v101
	v_sub_f32_e32 v118, v118, v101
	v_sub_f32_e32 v117, v117, v101
	v_sub_f32_e32 v116, v116, v101
	v_sub_f32_e32 v147, v147, v101
	v_sub_f32_e32 v146, v146, v101
	v_sub_f32_e32 v145, v145, v101
	v_sub_f32_e32 v144, v144, v101
	v_sub_f32_e32 v143, v143, v101
	v_sub_f32_e32 v142, v142, v101
	v_sub_f32_e32 v141, v141, v101
	v_sub_f32_e32 v140, v140, v101
	v_sub_f32_e32 v139, v139, v101
	v_sub_f32_e32 v138, v138, v101
	v_sub_f32_e32 v137, v137, v101
	v_sub_f32_e32 v136, v136, v101
	v_sub_f32_e32 v135, v135, v101
	v_sub_f32_e32 v134, v134, v101
	v_sub_f32_e32 v133, v133, v101
	v_sub_f32_e32 v132, v132, v101
	v_sub_f32_e32 v19, v19, v101
	v_sub_f32_e32 v18, v18, v101
	v_sub_f32_e32 v17, v17, v101
	v_sub_f32_e32 v16, v16, v101
	v_sub_f32_e32 v15, v15, v101
	v_sub_f32_e32 v14, v14, v101
	v_sub_f32_e32 v13, v13, v101
	v_sub_f32_e32 v12, v12, v101
	v_sub_f32_e32 v11, v11, v101
	v_sub_f32_e32 v10, v10, v101
	v_sub_f32_e32 v9, v9, v101
	v_sub_f32_e32 v8, v8, v101
	v_sub_f32_e32 v7, v7, v101
	v_sub_f32_e32 v6, v6, v101
	v_sub_f32_e32 v5, v5, v101
	v_sub_f32_e32 v4, v4, v101
	v_mul_f32_e32 v197, v197, v100
	s_branch .LBB0_408
.Lhot2_bias:
	ds_read2_b32 v[132:133], v192 offset1:1
	ds_read2_b32 v[134:135], v192 offset0:2 offset1:3
	ds_read2_b32 v[136:137], v192 offset0:8 offset1:9
	ds_read2_b32 v[138:139], v192 offset0:10 offset1:11
	ds_read2_b32 v[140:141], v192 offset0:16 offset1:17
	ds_read2_b32 v[142:143], v192 offset0:18 offset1:19
	ds_read2_b32 v[144:145], v192 offset0:24 offset1:25
	ds_read2_b32 v[146:147], v192 offset0:26 offset1:27
	ds_read2_b32 v[118:119], v192 offset0:32 offset1:33
	ds_read2_b32 v[120:121], v192 offset0:34 offset1:35
	ds_read2_b32 v[122:123], v192 offset0:40 offset1:41
	ds_read2_b32 v[164:165], v192 offset0:42 offset1:43
	s_waitcnt lgkmcnt(11)
	v_pk_add_f32 v[100:101], v[100:101], v[132:133]
	s_waitcnt lgkmcnt(5)
	v_pk_add_f32 v[112:113], v[112:113], v[144:145]
	v_pk_add_f32 v[110:111], v[110:111], v[142:143]
	v_pk_add_f32 v[108:109], v[108:109], v[140:141]
	ds_read2_b32 v[132:133], v192 offset0:48 offset1:49
	ds_read2_b32 v[140:141], v192 offset0:50 offset1:51
	ds_read2_b32 v[142:143], v192 offset0:56 offset1:57
	ds_read2_b32 v[144:145], v192 offset0:58 offset1:59
	s_waitcnt lgkmcnt(8)
	v_pk_add_f32 v[114:115], v[114:115], v[146:147]
	v_pk_add_f32 v[106:107], v[106:107], v[138:139]
	v_pk_add_f32 v[104:105], v[104:105], v[136:137]
	v_pk_add_f32 v[102:103], v[102:103], v[134:135]
	s_waitcnt lgkmcnt(7)
	v_pk_add_f32 v[84:85], v[84:85], v[118:119]
	s_waitcnt lgkmcnt(0)
	v_pk_add_f32 v[98:99], v[98:99], v[144:145]
	v_pk_add_f32 v[96:97], v[96:97], v[142:143]
	v_pk_add_f32 v[94:95], v[94:95], v[140:141]
	v_pk_add_f32 v[92:93], v[92:93], v[132:133]
	v_pk_add_f32 v[90:91], v[90:91], v[164:165]
	v_pk_add_f32 v[88:89], v[88:89], v[122:123]
	v_pk_add_f32 v[86:87], v[86:87], v[120:121]
	s_branch .Lat2_405
.Lhot2_mask:
	v_mov_b32_e32 v100, v245
	v_mov_b32_e32 v101, v245
	v_mov_b32_e32 v102, v245
	v_mov_b32_e32 v103, v245
	v_mov_b32_e32 v104, v245
	v_mov_b32_e32 v105, v245
	v_mov_b32_e32 v106, v245
	v_mov_b32_e32 v107, v245
	v_mov_b32_e32 v108, v245
	v_mov_b32_e32 v109, v245
	v_mov_b32_e32 v110, v245
	v_mov_b32_e32 v111, v245
	v_mov_b32_e32 v112, v245
	v_mov_b32_e32 v113, v245
	v_mov_b32_e32 v114, v245
	v_mov_b32_e32 v115, v245
	v_mov_b32_e32 v84, v245
	v_mov_b32_e32 v85, v245
	v_mov_b32_e32 v86, v245
	v_mov_b32_e32 v87, v245
	v_mov_b32_e32 v88, v245
	v_mov_b32_e32 v89, v245
	v_mov_b32_e32 v90, v245
	v_mov_b32_e32 v91, v245
	v_mov_b32_e32 v92, v245
	v_mov_b32_e32 v93, v245
	v_mov_b32_e32 v94, v245
	v_mov_b32_e32 v95, v245
	v_mov_b32_e32 v96, v245
	v_mov_b32_e32 v97, v245
	v_mov_b32_e32 v98, v245
	v_mov_b32_e32 v99, v245
	s_branch .Lat2_nomask
.Lhot2_resc:
	v_max_f32_e32 v116, v116, v116
	v_max_f32_e32 v117, 0, v116
	v_exp_f32_e64 v116, -v117
	v_sub_f32_e32 v115, v115, v117
	v_sub_f32_e32 v114, v114, v117
	v_sub_f32_e32 v113, v113, v117
	v_pk_mul_f32 v[82:83], v[82:83], v[116:117] op_sel_hi:[1,0]
	v_pk_mul_f32 v[80:81], v[80:81], v[116:117] op_sel_hi:[1,0]
	v_pk_mul_f32 v[78:79], v[78:79], v[116:117] op_sel_hi:[1,0]
	v_pk_mul_f32 v[76:77], v[76:77], v[116:117] op_sel_hi:[1,0]
	v_pk_mul_f32 v[74:75], v[74:75], v[116:117] op_sel_hi:[1,0]
	v_pk_mul_f32 v[72:73], v[72:73], v[116:117] op_sel_hi:[1,0]
	v_pk_mul_f32 v[70:71], v[70:71], v[116:117] op_sel_hi:[1,0]
	v_pk_mul_f32 v[68:69], v[68:69], v[116:117] op_sel_hi:[1,0]
	v_pk_mul_f32 v[66:67], v[66:67], v[116:117] op_sel_hi:[1,0]
	v_pk_mul_f32 v[64:65], v[64:65], v[116:117] op_sel_hi:[1,0]
	v_pk_mul_f32 v[62:63], v[62:63], v[116:117] op_sel_hi:[1,0]
	v_pk_mul_f32 v[60:61], v[60:61], v[116:117] op_sel_hi:[1,0]
	v_pk_mul_f32 v[58:59], v[58:59], v[116:117] op_sel_hi:[1,0]
	v_pk_mul_f32 v[56:57], v[56:57], v[116:117] op_sel_hi:[1,0]
	v_pk_mul_f32 v[54:55], v[54:55], v[116:117] op_sel_hi:[1,0]
	v_pk_mul_f32 v[52:53], v[52:53], v[116:117] op_sel_hi:[1,0]
	v_pk_mul_f32 v[50:51], v[50:51], v[116:117] op_sel_hi:[1,0]
	v_pk_mul_f32 v[48:49], v[48:49], v[116:117] op_sel_hi:[1,0]
	v_pk_mul_f32 v[46:47], v[46:47], v[116:117] op_sel_hi:[1,0]
	v_pk_mul_f32 v[44:45], v[44:45], v[116:117] op_sel_hi:[1,0]
	v_pk_mul_f32 v[42:43], v[42:43], v[116:117] op_sel_hi:[1,0]
	v_pk_mul_f32 v[40:41], v[40:41], v[116:117] op_sel_hi:[1,0]
	v_pk_mul_f32 v[38:39], v[38:39], v[116:117] op_sel_hi:[1,0]
	v_pk_mul_f32 v[36:37], v[36:37], v[116:117] op_sel_hi:[1,0]
	v_pk_mul_f32 v[34:35], v[34:35], v[116:117] op_sel_hi:[1,0]
	v_pk_mul_f32 v[32:33], v[32:33], v[116:117] op_sel_hi:[1,0]
	v_pk_mul_f32 v[30:31], v[30:31], v[116:117] op_sel_hi:[1,0]
	v_pk_mul_f32 v[28:29], v[28:29], v[116:117] op_sel_hi:[1,0]
	v_pk_mul_f32 v[26:27], v[26:27], v[116:117] op_sel_hi:[1,0]
	v_pk_mul_f32 v[24:25], v[24:25], v[116:117] op_sel_hi:[1,0]
	v_pk_mul_f32 v[22:23], v[22:23], v[116:117] op_sel_hi:[1,0]
	v_pk_mul_f32 v[20:21], v[20:21], v[116:117] op_sel_hi:[1,0]
	v_sub_f32_e32 v112, v112, v117
	v_sub_f32_e32 v111, v111, v117
	v_sub_f32_e32 v110, v110, v117
	v_sub_f32_e32 v109, v109, v117
	v_sub_f32_e32 v108, v108, v117
	v_sub_f32_e32 v107, v107, v117
	v_sub_f32_e32 v106, v106, v117
	v_sub_f32_e32 v105, v105, v117
	v_sub_f32_e32 v104, v104, v117
	v_sub_f32_e32 v103, v103, v117
	v_sub_f32_e32 v102, v102, v117
	v_sub_f32_e32 v101, v101, v117
	v_sub_f32_e32 v100, v100, v117
	v_sub_f32_e32 v99, v99, v117
	v_sub_f32_e32 v98, v98, v117
	v_sub_f32_e32 v97, v97, v117
	v_sub_f32_e32 v96, v96, v117
	v_sub_f32_e32 v95, v95, v117
	v_sub_f32_e32 v94, v94, v117
	v_sub_f32_e32 v93, v93, v117
	v_sub_f32_e32 v92, v92, v117
	v_sub_f32_e32 v91, v91, v117
	v_sub_f32_e32 v90, v90, v117
	v_sub_f32_e32 v89, v89, v117
	v_sub_f32_e32 v88, v88, v117
	v_sub_f32_e32 v87, v87, v117
	v_sub_f32_e32 v86, v86, v117
	v_sub_f32_e32 v85, v85, v117
	v_sub_f32_e32 v84, v84, v117
	v_sub_f32_e32 v19, v19, v117
	v_sub_f32_e32 v18, v18, v117
	v_sub_f32_e32 v17, v17, v117
	v_sub_f32_e32 v16, v16, v117
	v_sub_f32_e32 v15, v15, v117
	v_sub_f32_e32 v14, v14, v117
	v_sub_f32_e32 v13, v13, v117
	v_sub_f32_e32 v12, v12, v117
	v_sub_f32_e32 v11, v11, v117
	v_sub_f32_e32 v10, v10, v117
	v_sub_f32_e32 v9, v9, v117
	v_sub_f32_e32 v8, v8, v117
	v_sub_f32_e32 v7, v7, v117
	v_sub_f32_e32 v6, v6, v117
	v_sub_f32_e32 v5, v5, v117
	v_sub_f32_e32 v4, v4, v117
	v_mul_f32_e32 v197, v197, v116
	s_branch .Lat2_408
.Lrot2_w0:
	s_waitcnt vmcnt(0) lgkmcnt(0)
	s_branch .Lrot2_bar
